# GEMM compute blocks: first 9 hoisted address/load lines placed between the initial fragment ds_reads and the first lgkmcnt wait (fills the LDS latency at the block head)
# baseline (speedup 1.0000x reference)
.LcL_20:
	s_waitcnt lgkmcnt(0)
	s_barrier
	s_setprio 2
	ds_read_b128 v[190:193], v179 offset:36864
	ds_read_b128 v[194:197], v179 offset:41472
	ds_read_b128 v[206:209], v178
	ds_read_b128 v[216:219], v178 offset:4608
	ds_read_b128 v[236:239], v178 offset:9216
	ds_read_b128 v[240:243], v178 offset:13824
	ds_read_b128 v[244:247], v178 offset:32
	s_ashr_i32 s1, s0, 31
	s_lshl_b64 s[6:7], s[0:1], 7
	v_lshl_add_u64 v[154:155], v[180:181], 0, s[6:7]
	v_add_co_u32_e32 v130, vcc, 0x2c000, v154
	v_lshl_add_u64 v[170:171], v[182:183], 0, s[6:7]
	s_nop 0
	v_addc_co_u32_e32 v131, vcc, 0, v155, vcc
	v_add_co_u32_e32 v134, vcc, 0x58000, v154
	global_load_dwordx4 v[142:145], v[154:155], off
	s_waitcnt lgkmcnt(4)
	v_mfma_f32_32x32x16_bf16 v[114:129], v[190:193], v[206:209], v[114:129]
	s_nop 0
	global_load_dwordx4 v[130:133], v[130:131], off
	v_addc_co_u32_e32 v135, vcc, 0, v155, vcc
	v_mfma_f32_32x32x16_bf16 v[98:113], v[194:197], v[206:209], v[98:113]
	v_add_co_u32_e32 v138, vcc, 0x84000, v154
	s_add_i32 s0, s0, 1
	s_nop 0
	ds_read_b128 v[206:209], v178 offset:4640
	ds_read_b128 v[198:201], v179 offset:36896
	ds_read_b128 v[202:205], v179 offset:41504
	s_waitcnt lgkmcnt(6)
	v_mfma_f32_32x32x16_bf16 v[82:97], v[190:193], v[216:219], v[82:97]
	v_addc_co_u32_e32 v139, vcc, 0, v155, vcc
	v_add_co_u32_e32 v146, vcc, 0xb0000, v154
	global_load_dwordx4 v[134:137], v[134:135], off
	v_mfma_f32_32x32x16_bf16 v[66:81], v[194:197], v[216:219], v[66:81]
	s_nop 0
	global_load_dwordx4 v[138:141], v[138:139], off
	v_addc_co_u32_e32 v147, vcc, 0, v155, vcc
	ds_read_b128 v[216:219], v178 offset:9248
	s_waitcnt lgkmcnt(6)
	v_mfma_f32_32x32x16_bf16 v[50:65], v[190:193], v[236:239], v[50:65]
	v_add_co_u32_e32 v150, vcc, 0xdc000, v154
	s_nop 0
	v_addc_co_u32_e32 v151, vcc, 0, v155, vcc
	v_mfma_f32_32x32x16_bf16 v[34:49], v[194:197], v[236:239], v[34:49]
	v_add_co_u32_e32 v156, vcc, 0x108000, v154
	global_load_dwordx4 v[146:149], v[146:147], off
	s_nop 0
	ds_read_b128 v[236:239], v178 offset:13856
	s_waitcnt lgkmcnt(6)
	v_mfma_f32_32x32x16_bf16 v[18:33], v[190:193], v[240:243], v[18:33]
	global_load_dwordx4 v[150:153], v[150:151], off
	v_addc_co_u32_e32 v157, vcc, 0, v155, vcc
	v_add_co_u32_e32 v158, vcc, 0x134000, v154
	v_mfma_f32_32x32x16_bf16 v[2:17], v[194:197], v[240:243], v[2:17]
	s_nop 1
	v_addc_co_u32_e32 v159, vcc, 0, v155, vcc
	v_add_co_u32_e32 v166, vcc, 0x2c000, v170
	ds_read_b128 v[240:243], v178 offset:64
	s_waitcnt lgkmcnt(3)
	v_mfma_f32_32x32x16_bf16 v[114:129], v[198:201], v[244:247], v[114:129]
	global_load_dwordx4 v[154:157], v[156:157], off
	s_nop 0
	global_load_dwordx4 v[158:161], v[158:159], off
	v_mfma_f32_32x32x16_bf16 v[98:113], v[202:205], v[244:247], v[98:113]
	v_addc_co_u32_e32 v167, vcc, 0, v171, vcc
	v_add_co_u32_e32 v172, vcc, 0x58000, v170
	global_load_dwordx4 v[162:165], v[170:171], off
	ds_read_b128 v[244:247], v178 offset:4672
	ds_read_b128 v[190:193], v179 offset:36928
	ds_read_b128 v[194:197], v179 offset:41536
	v_mfma_f32_32x32x16_bf16 v[82:97], v[198:201], v[206:209], v[82:97]
	s_nop 0
	global_load_dwordx4 v[166:169], v[166:167], off
	v_addc_co_u32_e32 v173, vcc, 0, v171, vcc
	v_mfma_f32_32x32x16_bf16 v[66:81], v[202:205], v[206:209], v[66:81]
	v_add_co_u32_e32 v174, vcc, 0x84000, v170
	s_nop 1
	v_addc_co_u32_e32 v175, vcc, 0, v171, vcc
	ds_read_b128 v[206:209], v178 offset:9280
	s_waitcnt lgkmcnt(6)
	v_mfma_f32_32x32x16_bf16 v[50:65], v[198:201], v[216:219], v[50:65]
	global_load_dwordx4 v[170:173], v[172:173], off
	s_nop 0
	global_load_dwordx4 v[174:177], v[174:175], off
	v_mfma_f32_32x32x16_bf16 v[34:49], v[202:205], v[216:219], v[34:49]
	s_cmp_lg_u32 s0, 44
	ds_read_b128 v[216:219], v178 offset:13888
	s_waitcnt lgkmcnt(6)
	v_mfma_f32_32x32x16_bf16 v[18:33], v[198:201], v[236:239], v[18:33]
	v_mfma_f32_32x32x16_bf16 v[2:17], v[202:205], v[236:239], v[2:17]
	ds_read_b128 v[236:239], v178 offset:96
	s_waitcnt lgkmcnt(3)
	v_mfma_f32_32x32x16_bf16 v[114:129], v[190:193], v[240:243], v[114:129]
	v_mfma_f32_32x32x16_bf16 v[98:113], v[194:197], v[240:243], v[98:113]
	ds_read_b128 v[240:243], v178 offset:4704
	ds_read_b128 v[198:201], v179 offset:36960
	ds_read_b128 v[202:205], v179 offset:41568
	v_mfma_f32_32x32x16_bf16 v[82:97], v[190:193], v[244:247], v[82:97]
	v_mfma_f32_32x32x16_bf16 v[66:81], v[194:197], v[244:247], v[66:81]
	ds_read_b128 v[244:247], v178 offset:9312
	s_waitcnt lgkmcnt(6)
	v_mfma_f32_32x32x16_bf16 v[50:65], v[190:193], v[206:209], v[50:65]
	v_mfma_f32_32x32x16_bf16 v[34:49], v[194:197], v[206:209], v[34:49]
	ds_read_b128 v[206:209], v178 offset:13920
	s_waitcnt lgkmcnt(6)
	v_mfma_f32_32x32x16_bf16 v[18:33], v[190:193], v[216:219], v[18:33]
	v_mfma_f32_32x32x16_bf16 v[2:17], v[194:197], v[216:219], v[2:17]
	s_waitcnt lgkmcnt(2)
	v_mfma_f32_32x32x16_bf16 v[114:129], v[198:201], v[236:239], v[114:129]
	v_mfma_f32_32x32x16_bf16 v[98:113], v[202:205], v[236:239], v[98:113]
	v_mfma_f32_32x32x16_bf16 v[82:97], v[198:201], v[240:243], v[82:97]
	v_mfma_f32_32x32x16_bf16 v[66:81], v[202:205], v[240:243], v[66:81]
	s_waitcnt lgkmcnt(1)
	v_mfma_f32_32x32x16_bf16 v[50:65], v[198:201], v[244:247], v[50:65]
	v_mfma_f32_32x32x16_bf16 v[34:49], v[202:205], v[244:247], v[34:49]
	s_waitcnt lgkmcnt(0)
	v_mfma_f32_32x32x16_bf16 v[18:33], v[198:201], v[206:209], v[18:33]
	v_mfma_f32_32x32x16_bf16 v[2:17], v[202:205], v[206:209], v[2:17]
	s_setprio 0
	s_cbranch_scc1 .Ltail_20
	s_add_i32 s2, s2, 1
	s_cmp_ge_i32 s2, s4
	s_cbranch_scc1 .Lz_20
	s_mul_i32 s0, s2, s82
	s_add_i32 s0, s0, s63
	s_ashr_i32 s1, s0, 31
	s_lshr_b32 s1, s1, 28
	s_add_i32 s1, s0, s1
	s_ashr_i32 s6, s1, 4
	s_and_b32 s1, s1, -16
	s_sub_i32 s0, s0, s1
	s_lshl_b32 s1, s6, 1
	s_and_b32 s6, s0, 1
	s_or_b32 s6, s6, s1
	s_lshr_b32 s7, s0, 1
	v_readlane_b32 s0, v252, 35
	s_sub_i32 s8, 0x7f, s6
	v_readlane_b32 s1, v252, 36
	s_and_b64 s[0:1], s[0:1], exec
	s_mul_i32 s0, s7, 0x58000
	s_cselect_b32 s6, s8, s6
	s_ashr_i32 s1, s0, 31
	v_mov_b32_e32 v0, 0x160000
	v_mad_i64_i32 v[180:181], s[6:7], s6, v0, v[186:187]
	v_lshl_add_u64 v[182:183], s[0:1], 1, v[188:189]

.LcL_34:
	s_waitcnt lgkmcnt(0)
	s_barrier
	s_setprio 2
	ds_read_b128 v[190:193], v179 offset:36864
	ds_read_b128 v[194:197], v179 offset:41472
	ds_read_b128 v[206:209], v178
	ds_read_b128 v[216:219], v178 offset:4608
	ds_read_b128 v[236:239], v178 offset:9216
	ds_read_b128 v[240:243], v178 offset:13824
	ds_read_b128 v[244:247], v178 offset:32
	s_ashr_i32 s1, s0, 31
	s_lshl_b64 s[6:7], s[0:1], 7
	v_lshl_add_u64 v[154:155], v[180:181], 0, s[6:7]
	v_add_co_u32_e32 v130, vcc, 0x10000, v154
	v_lshl_add_u64 v[170:171], v[182:183], 0, s[6:7]
	s_nop 0
	v_addc_co_u32_e32 v131, vcc, 0, v155, vcc
	v_add_co_u32_e32 v134, vcc, 0x20000, v154
	global_load_dwordx4 v[142:145], v[154:155], off
	s_waitcnt lgkmcnt(4)
	v_mfma_f32_32x32x16_bf16 v[114:129], v[190:193], v[206:209], v[114:129]
	s_nop 0
	global_load_dwordx4 v[130:133], v[130:131], off
	v_addc_co_u32_e32 v135, vcc, 0, v155, vcc
	v_mfma_f32_32x32x16_bf16 v[98:113], v[194:197], v[206:209], v[98:113]
	v_add_co_u32_e32 v138, vcc, 0x30000, v154
	s_add_i32 s0, s0, 1
	s_nop 0
	ds_read_b128 v[206:209], v178 offset:4640
	ds_read_b128 v[198:201], v179 offset:36896
	ds_read_b128 v[202:205], v179 offset:41504
	s_waitcnt lgkmcnt(6)
	v_mfma_f32_32x32x16_bf16 v[82:97], v[190:193], v[216:219], v[82:97]
	v_addc_co_u32_e32 v139, vcc, 0, v155, vcc
	v_add_co_u32_e32 v146, vcc, 0x40000, v154
	global_load_dwordx4 v[134:137], v[134:135], off
	v_mfma_f32_32x32x16_bf16 v[66:81], v[194:197], v[216:219], v[66:81]
	s_nop 0
	global_load_dwordx4 v[138:141], v[138:139], off
	v_addc_co_u32_e32 v147, vcc, 0, v155, vcc
	ds_read_b128 v[216:219], v178 offset:9248
	s_waitcnt lgkmcnt(6)
	v_mfma_f32_32x32x16_bf16 v[50:65], v[190:193], v[236:239], v[50:65]
	v_add_co_u32_e32 v150, vcc, 0x50000, v154
	s_nop 0
	v_addc_co_u32_e32 v151, vcc, 0, v155, vcc
	v_mfma_f32_32x32x16_bf16 v[34:49], v[194:197], v[236:239], v[34:49]
	v_add_co_u32_e32 v156, vcc, 0x60000, v154
	global_load_dwordx4 v[146:149], v[146:147], off
	s_nop 0
	ds_read_b128 v[236:239], v178 offset:13856
	s_waitcnt lgkmcnt(6)
	v_mfma_f32_32x32x16_bf16 v[18:33], v[190:193], v[240:243], v[18:33]
	global_load_dwordx4 v[150:153], v[150:151], off
	v_addc_co_u32_e32 v157, vcc, 0, v155, vcc
	v_add_co_u32_e32 v158, vcc, 0x70000, v154
	v_mfma_f32_32x32x16_bf16 v[2:17], v[194:197], v[240:243], v[2:17]
	s_nop 1
	v_addc_co_u32_e32 v159, vcc, 0, v155, vcc
	v_add_co_u32_e32 v166, vcc, 0x10000, v170
	ds_read_b128 v[240:243], v178 offset:64
	s_waitcnt lgkmcnt(3)
	v_mfma_f32_32x32x16_bf16 v[114:129], v[198:201], v[244:247], v[114:129]
	global_load_dwordx4 v[154:157], v[156:157], off
	s_nop 0
	global_load_dwordx4 v[158:161], v[158:159], off
	v_mfma_f32_32x32x16_bf16 v[98:113], v[202:205], v[244:247], v[98:113]
	v_addc_co_u32_e32 v167, vcc, 0, v171, vcc
	v_add_co_u32_e32 v172, vcc, 0x20000, v170
	global_load_dwordx4 v[162:165], v[170:171], off
	ds_read_b128 v[244:247], v178 offset:4672
	ds_read_b128 v[190:193], v179 offset:36928
	ds_read_b128 v[194:197], v179 offset:41536
	v_mfma_f32_32x32x16_bf16 v[82:97], v[198:201], v[206:209], v[82:97]
	s_nop 0
	global_load_dwordx4 v[166:169], v[166:167], off
	v_addc_co_u32_e32 v173, vcc, 0, v171, vcc
	v_mfma_f32_32x32x16_bf16 v[66:81], v[202:205], v[206:209], v[66:81]
	v_add_co_u32_e32 v174, vcc, 0x30000, v170
	s_nop 1
	v_addc_co_u32_e32 v175, vcc, 0, v171, vcc
	ds_read_b128 v[206:209], v178 offset:9280
	s_waitcnt lgkmcnt(6)
	v_mfma_f32_32x32x16_bf16 v[50:65], v[198:201], v[216:219], v[50:65]
	global_load_dwordx4 v[170:173], v[172:173], off
	s_nop 0
	global_load_dwordx4 v[174:177], v[174:175], off
	v_mfma_f32_32x32x16_bf16 v[34:49], v[202:205], v[216:219], v[34:49]
	s_cmp_lg_u32 s0, 16
	ds_read_b128 v[216:219], v178 offset:13888
	s_waitcnt lgkmcnt(6)
	v_mfma_f32_32x32x16_bf16 v[18:33], v[198:201], v[236:239], v[18:33]
	v_mfma_f32_32x32x16_bf16 v[2:17], v[202:205], v[236:239], v[2:17]
	ds_read_b128 v[236:239], v178 offset:96
	s_waitcnt lgkmcnt(3)
	v_mfma_f32_32x32x16_bf16 v[114:129], v[190:193], v[240:243], v[114:129]
	v_mfma_f32_32x32x16_bf16 v[98:113], v[194:197], v[240:243], v[98:113]
	ds_read_b128 v[240:243], v178 offset:4704
	ds_read_b128 v[198:201], v179 offset:36960
	ds_read_b128 v[202:205], v179 offset:41568
	v_mfma_f32_32x32x16_bf16 v[82:97], v[190:193], v[244:247], v[82:97]
	v_mfma_f32_32x32x16_bf16 v[66:81], v[194:197], v[244:247], v[66:81]
	ds_read_b128 v[244:247], v178 offset:9312
	s_waitcnt lgkmcnt(6)
	v_mfma_f32_32x32x16_bf16 v[50:65], v[190:193], v[206:209], v[50:65]
	v_mfma_f32_32x32x16_bf16 v[34:49], v[194:197], v[206:209], v[34:49]
	ds_read_b128 v[206:209], v178 offset:13920
	s_waitcnt lgkmcnt(6)
	v_mfma_f32_32x32x16_bf16 v[18:33], v[190:193], v[216:219], v[18:33]
	v_mfma_f32_32x32x16_bf16 v[2:17], v[194:197], v[216:219], v[2:17]
	s_waitcnt lgkmcnt(2)
	v_mfma_f32_32x32x16_bf16 v[114:129], v[198:201], v[236:239], v[114:129]
	v_mfma_f32_32x32x16_bf16 v[98:113], v[202:205], v[236:239], v[98:113]
	v_mfma_f32_32x32x16_bf16 v[82:97], v[198:201], v[240:243], v[82:97]
	v_mfma_f32_32x32x16_bf16 v[66:81], v[202:205], v[240:243], v[66:81]
	s_waitcnt lgkmcnt(1)
	v_mfma_f32_32x32x16_bf16 v[50:65], v[198:201], v[244:247], v[50:65]
	v_mfma_f32_32x32x16_bf16 v[34:49], v[202:205], v[244:247], v[34:49]
	s_waitcnt lgkmcnt(0)
	v_mfma_f32_32x32x16_bf16 v[18:33], v[198:201], v[206:209], v[18:33]
	v_mfma_f32_32x32x16_bf16 v[2:17], v[202:205], v[206:209], v[2:17]
	s_setprio 0
	s_cbranch_scc1 .Ltail_34
	s_add_i32 s2, s2, 1
	s_cmp_ge_i32 s2, s4
	s_cbranch_scc1 .Lz_34
	s_mul_i32 s0, s2, s82
	s_add_i32 s0, s0, s63
	s_mul_hi_i32 s1, s0, 0x2e8ba2e9
	s_lshr_b32 s6, s1, 31
	s_ashr_i32 s1, s1, 4
	s_add_i32 s1, s1, s6
	s_mul_i32 s6, s1, 0x58
	s_sub_i32 s0, s0, s6
	s_lshl_b32 s1, s1, 1
	s_and_b32 s6, s0, 1
	s_or_b32 s1, s6, s1
	v_readlane_b32 s6, v252, 35
	s_ashr_i32 s0, s0, 1
	s_sub_i32 s8, 0x7f, s1
	v_readlane_b32 s7, v252, 36
	s_and_b64 s[6:7], s[6:7], exec
	s_cselect_b32 s6, s8, s1
	s_ashr_i32 s7, s6, 31
	s_ashr_i32 s1, s0, 31
	s_lshl_b64 s[6:7], s[6:7], 19
	s_lshl_b64 s[0:1], s[0:1], 18
	v_lshl_add_u64 v[180:181], v[186:187], 0, s[6:7]
	v_lshl_add_u64 v[182:183], v[188:189], 0, s[0:1]

.LcL_62:
	s_waitcnt lgkmcnt(0)
	s_barrier
	s_setprio 2
	ds_read_b128 v[190:193], v179 offset:36864
	ds_read_b128 v[194:197], v179 offset:41472
	ds_read_b128 v[206:209], v178
	ds_read_b128 v[216:219], v178 offset:4608
	ds_read_b128 v[236:239], v178 offset:9216
	ds_read_b128 v[240:243], v178 offset:13824
	ds_read_b128 v[244:247], v178 offset:32
	s_ashr_i32 s1, s0, 31
	s_lshl_b64 s[4:5], s[0:1], 7
	v_lshl_add_u64 v[154:155], v[180:181], 0, s[4:5]
	v_add_co_u32_e32 v130, vcc, 0x10000, v154
	v_lshl_add_u64 v[170:171], v[182:183], 0, s[4:5]
	s_nop 0
	v_addc_co_u32_e32 v131, vcc, 0, v155, vcc
	v_add_co_u32_e32 v134, vcc, 0x20000, v154
	global_load_dwordx4 v[142:145], v[154:155], off
	s_waitcnt lgkmcnt(4)
	v_mfma_f32_32x32x16_bf16 v[114:129], v[190:193], v[206:209], v[114:129]
	s_nop 0
	global_load_dwordx4 v[130:133], v[130:131], off
	v_addc_co_u32_e32 v135, vcc, 0, v155, vcc
	v_mfma_f32_32x32x16_bf16 v[98:113], v[194:197], v[206:209], v[98:113]
	v_add_co_u32_e32 v138, vcc, 0x30000, v154
	s_add_i32 s0, s0, 1
	s_nop 0
	ds_read_b128 v[206:209], v178 offset:4640
	ds_read_b128 v[198:201], v179 offset:36896
	ds_read_b128 v[202:205], v179 offset:41504
	s_waitcnt lgkmcnt(6)
	v_mfma_f32_32x32x16_bf16 v[82:97], v[190:193], v[216:219], v[82:97]
	v_addc_co_u32_e32 v139, vcc, 0, v155, vcc
	v_add_co_u32_e32 v146, vcc, 0x40000, v154
	global_load_dwordx4 v[134:137], v[134:135], off
	v_mfma_f32_32x32x16_bf16 v[66:81], v[194:197], v[216:219], v[66:81]
	s_nop 0
	global_load_dwordx4 v[138:141], v[138:139], off
	v_addc_co_u32_e32 v147, vcc, 0, v155, vcc
	ds_read_b128 v[216:219], v178 offset:9248
	s_waitcnt lgkmcnt(6)
	v_mfma_f32_32x32x16_bf16 v[50:65], v[190:193], v[236:239], v[50:65]
	v_add_co_u32_e32 v150, vcc, 0x50000, v154
	s_nop 0
	v_addc_co_u32_e32 v151, vcc, 0, v155, vcc
	v_mfma_f32_32x32x16_bf16 v[34:49], v[194:197], v[236:239], v[34:49]
	v_add_co_u32_e32 v156, vcc, 0x60000, v154
	global_load_dwordx4 v[146:149], v[146:147], off
	s_nop 0
	ds_read_b128 v[236:239], v178 offset:13856
	s_waitcnt lgkmcnt(6)
	v_mfma_f32_32x32x16_bf16 v[18:33], v[190:193], v[240:243], v[18:33]
	global_load_dwordx4 v[150:153], v[150:151], off
	v_addc_co_u32_e32 v157, vcc, 0, v155, vcc
	v_add_co_u32_e32 v158, vcc, 0x70000, v154
	v_mfma_f32_32x32x16_bf16 v[2:17], v[194:197], v[240:243], v[2:17]
	s_nop 1
	v_addc_co_u32_e32 v159, vcc, 0, v155, vcc
	v_add_co_u32_e32 v166, vcc, 0x10000, v170
	ds_read_b128 v[240:243], v178 offset:64
	s_waitcnt lgkmcnt(3)
	v_mfma_f32_32x32x16_bf16 v[114:129], v[198:201], v[244:247], v[114:129]
	global_load_dwordx4 v[154:157], v[156:157], off
	s_nop 0
	global_load_dwordx4 v[158:161], v[158:159], off
	v_mfma_f32_32x32x16_bf16 v[98:113], v[202:205], v[244:247], v[98:113]
	v_addc_co_u32_e32 v167, vcc, 0, v171, vcc
	v_add_co_u32_e32 v172, vcc, 0x20000, v170
	global_load_dwordx4 v[162:165], v[170:171], off
	ds_read_b128 v[244:247], v178 offset:4672
	ds_read_b128 v[190:193], v179 offset:36928
	ds_read_b128 v[194:197], v179 offset:41536
	v_mfma_f32_32x32x16_bf16 v[82:97], v[198:201], v[206:209], v[82:97]
	s_nop 0
	global_load_dwordx4 v[166:169], v[166:167], off
	v_addc_co_u32_e32 v173, vcc, 0, v171, vcc
	v_mfma_f32_32x32x16_bf16 v[66:81], v[202:205], v[206:209], v[66:81]
	v_add_co_u32_e32 v174, vcc, 0x30000, v170
	s_nop 1
	v_addc_co_u32_e32 v175, vcc, 0, v171, vcc
	ds_read_b128 v[206:209], v178 offset:9280
	s_waitcnt lgkmcnt(6)
	v_mfma_f32_32x32x16_bf16 v[50:65], v[198:201], v[216:219], v[50:65]
	global_load_dwordx4 v[170:173], v[172:173], off
	s_nop 0
	global_load_dwordx4 v[174:177], v[174:175], off
	v_mfma_f32_32x32x16_bf16 v[34:49], v[202:205], v[216:219], v[34:49]
	s_cmp_lg_u32 s0, 16
	ds_read_b128 v[216:219], v178 offset:13888
	s_waitcnt lgkmcnt(6)
	v_mfma_f32_32x32x16_bf16 v[18:33], v[198:201], v[236:239], v[18:33]
	v_mfma_f32_32x32x16_bf16 v[2:17], v[202:205], v[236:239], v[2:17]
	ds_read_b128 v[236:239], v178 offset:96
	s_waitcnt lgkmcnt(3)
	v_mfma_f32_32x32x16_bf16 v[114:129], v[190:193], v[240:243], v[114:129]
	v_mfma_f32_32x32x16_bf16 v[98:113], v[194:197], v[240:243], v[98:113]
	ds_read_b128 v[240:243], v178 offset:4704
	ds_read_b128 v[198:201], v179 offset:36960
	ds_read_b128 v[202:205], v179 offset:41568
	v_mfma_f32_32x32x16_bf16 v[82:97], v[190:193], v[244:247], v[82:97]
	v_mfma_f32_32x32x16_bf16 v[66:81], v[194:197], v[244:247], v[66:81]
	ds_read_b128 v[244:247], v178 offset:9312
	s_waitcnt lgkmcnt(6)
	v_mfma_f32_32x32x16_bf16 v[50:65], v[190:193], v[206:209], v[50:65]
	v_mfma_f32_32x32x16_bf16 v[34:49], v[194:197], v[206:209], v[34:49]
	ds_read_b128 v[206:209], v178 offset:13920
	s_waitcnt lgkmcnt(6)
	v_mfma_f32_32x32x16_bf16 v[18:33], v[190:193], v[216:219], v[18:33]
	v_mfma_f32_32x32x16_bf16 v[2:17], v[194:197], v[216:219], v[2:17]
	s_waitcnt lgkmcnt(2)
	v_mfma_f32_32x32x16_bf16 v[114:129], v[198:201], v[236:239], v[114:129]
	v_mfma_f32_32x32x16_bf16 v[98:113], v[202:205], v[236:239], v[98:113]
	v_mfma_f32_32x32x16_bf16 v[82:97], v[198:201], v[240:243], v[82:97]
	v_mfma_f32_32x32x16_bf16 v[66:81], v[202:205], v[240:243], v[66:81]
	s_waitcnt lgkmcnt(1)
	v_mfma_f32_32x32x16_bf16 v[50:65], v[198:201], v[244:247], v[50:65]
	v_mfma_f32_32x32x16_bf16 v[34:49], v[202:205], v[244:247], v[34:49]
	s_waitcnt lgkmcnt(0)
	v_mfma_f32_32x32x16_bf16 v[18:33], v[198:201], v[206:209], v[18:33]
	v_mfma_f32_32x32x16_bf16 v[2:17], v[202:205], v[206:209], v[2:17]
	s_setprio 0
	s_cbranch_scc1 .Ltail_62
	s_add_i32 s2, s2, 1
	s_cmp_ge_i32 s2, s6
	s_cbranch_scc1 .Lz_62
	s_mul_i32 s0, s2, s82
	s_add_i32 s0, s0, s63
	s_ashr_i32 s1, s0, 31
	s_lshr_b32 s1, s1, 28
	s_add_i32 s1, s0, s1
	s_ashr_i32 s4, s1, 4
	s_and_b32 s1, s1, -16
	s_sub_i32 s0, s0, s1
	s_lshl_b32 s1, s4, 1
	s_and_b32 s4, s0, 1
	s_or_b32 s1, s4, s1
	v_readlane_b32 s4, v252, 35
	s_ashr_i32 s0, s0, 1
	s_sub_i32 s8, 0x7f, s1
	v_readlane_b32 s5, v252, 36
	s_and_b64 s[4:5], s[4:5], exec
	s_cselect_b32 s4, s8, s1
	s_ashr_i32 s5, s4, 31
	s_ashr_i32 s1, s0, 31
	s_lshl_b64 s[4:5], s[4:5], 19
	s_lshl_b64 s[0:1], s[0:1], 18
	v_lshl_add_u64 v[180:181], v[186:187], 0, s[4:5]
	v_lshl_add_u64 v[182:183], v[188:189], 0, s[0:1]

.LcL_92:
	s_waitcnt lgkmcnt(0)
	s_barrier
	s_setprio 2
	ds_read_b128 v[190:193], v181 offset:36864
	ds_read_b128 v[194:197], v181 offset:41472
	ds_read_b128 v[206:209], v180
	ds_read_b128 v[216:219], v180 offset:4608
	ds_read_b128 v[236:239], v180 offset:9216
	ds_read_b128 v[240:243], v180 offset:13824
	ds_read_b128 v[244:247], v180 offset:32
	s_ashr_i32 s9, s8, 31
	s_lshl_b64 s[12:13], s[10:11], 6
	s_lshl_b64 s[4:5], s[8:9], 7
	v_lshl_add_u64 v[138:139], v[186:187], 0, s[12:13]
	v_lshl_add_u64 v[134:135], v[138:139], 0, s[4:5]
	v_lshl_add_u64 v[138:139], v[138:139], 0, s[12:13]
	v_lshl_add_u64 v[146:147], v[138:139], 0, s[12:13]
	v_lshl_add_u64 v[142:143], v[146:147], 0, s[4:5]
	v_lshl_add_u64 v[146:147], v[146:147], 0, s[12:13]
	s_waitcnt lgkmcnt(4)
	v_mfma_f32_32x32x16_bf16 v[114:129], v[190:193], v[206:209], v[114:129]
	v_lshl_add_u64 v[154:155], v[146:147], 0, s[12:13]
	v_lshl_add_u64 v[150:151], v[154:155], 0, s[4:5]
	v_lshl_add_u64 v[154:155], v[154:155], 0, s[12:13]
	v_mfma_f32_32x32x16_bf16 v[98:113], v[194:197], v[206:209], v[98:113]
	v_lshl_add_u64 v[156:157], v[154:155], 0, s[4:5]
	v_lshl_add_u64 v[154:155], v[154:155], 0, s[12:13]
	s_lshl_b64 s[12:13], s[10:11], 6
	ds_read_b128 v[206:209], v180 offset:4640
	ds_read_b128 v[198:201], v181 offset:36896
	ds_read_b128 v[202:205], v181 offset:41504
	s_waitcnt lgkmcnt(6)
	v_mfma_f32_32x32x16_bf16 v[82:97], v[190:193], v[216:219], v[82:97]
	v_lshl_add_u64 v[170:171], v[188:189], 0, s[12:13]
	v_lshl_add_u64 v[166:167], v[170:171], 0, s[4:5]
	v_lshl_add_u64 v[170:171], v[170:171], 0, s[12:13]
	v_mfma_f32_32x32x16_bf16 v[66:81], v[194:197], v[216:219], v[66:81]
	v_lshl_add_u64 v[172:173], v[170:171], 0, s[4:5]
	v_lshl_add_u64 v[170:171], v[170:171], 0, s[12:13]
	v_lshl_add_u64 v[130:131], v[186:187], 0, s[4:5]
	ds_read_b128 v[216:219], v180 offset:9248
	s_waitcnt lgkmcnt(6)
	v_mfma_f32_32x32x16_bf16 v[50:65], v[190:193], v[236:239], v[50:65]
	v_lshl_add_u64 v[140:141], v[138:139], 0, s[4:5]
	v_lshl_add_u64 v[148:149], v[146:147], 0, s[4:5]
	v_lshl_add_u64 v[158:159], v[154:155], 0, s[4:5]
	v_mfma_f32_32x32x16_bf16 v[34:49], v[194:197], v[236:239], v[34:49]
	v_lshl_add_u64 v[162:163], v[188:189], 0, s[4:5]
	v_lshl_add_u64 v[174:175], v[170:171], 0, s[4:5]
	global_load_dwordx4 v[130:133], v[130:131], off
	ds_read_b128 v[236:239], v180 offset:13856
	s_waitcnt lgkmcnt(6)
	v_mfma_f32_32x32x16_bf16 v[18:33], v[190:193], v[240:243], v[18:33]
	s_nop 0
	global_load_dwordx4 v[134:137], v[134:135], off
	s_nop 0
	v_mfma_f32_32x32x16_bf16 v[2:17], v[194:197], v[240:243], v[2:17]
	global_load_dwordx4 v[138:141], v[140:141], off
	s_nop 0
	global_load_dwordx4 v[142:145], v[142:143], off
	ds_read_b128 v[240:243], v180 offset:64
	s_waitcnt lgkmcnt(3)
	v_mfma_f32_32x32x16_bf16 v[114:129], v[198:201], v[244:247], v[114:129]
	s_nop 0
	global_load_dwordx4 v[146:149], v[148:149], off
	s_nop 0
	v_mfma_f32_32x32x16_bf16 v[98:113], v[202:205], v[244:247], v[98:113]
	global_load_dwordx4 v[150:153], v[150:151], off
	s_nop 0
	global_load_dwordx4 v[154:157], v[156:157], off
	ds_read_b128 v[244:247], v180 offset:4672
	ds_read_b128 v[190:193], v181 offset:36928
	ds_read_b128 v[194:197], v181 offset:41536
	v_mfma_f32_32x32x16_bf16 v[82:97], v[198:201], v[206:209], v[82:97]
	s_nop 0
	global_load_dwordx4 v[158:161], v[158:159], off
	s_nop 0
	v_mfma_f32_32x32x16_bf16 v[66:81], v[202:205], v[206:209], v[66:81]
	global_load_dwordx4 v[162:165], v[162:163], off
	s_nop 0
	global_load_dwordx4 v[166:169], v[166:167], off
	ds_read_b128 v[206:209], v180 offset:9280
	s_waitcnt lgkmcnt(6)
	v_mfma_f32_32x32x16_bf16 v[50:65], v[198:201], v[216:219], v[50:65]
	s_nop 0
	global_load_dwordx4 v[170:173], v[172:173], off
	s_nop 0
	v_mfma_f32_32x32x16_bf16 v[34:49], v[202:205], v[216:219], v[34:49]
	global_load_dwordx4 v[174:177], v[174:175], off
	s_add_i32 s8, s8, 1
	s_cmp_lg_u32 s8, s19
	ds_read_b128 v[216:219], v180 offset:13888
	s_waitcnt lgkmcnt(6)
	v_mfma_f32_32x32x16_bf16 v[18:33], v[198:201], v[236:239], v[18:33]
	v_mfma_f32_32x32x16_bf16 v[2:17], v[202:205], v[236:239], v[2:17]
	ds_read_b128 v[236:239], v180 offset:96
	s_waitcnt lgkmcnt(3)
	v_mfma_f32_32x32x16_bf16 v[114:129], v[190:193], v[240:243], v[114:129]
	v_mfma_f32_32x32x16_bf16 v[98:113], v[194:197], v[240:243], v[98:113]
	ds_read_b128 v[240:243], v180 offset:4704
	ds_read_b128 v[198:201], v181 offset:36960
	ds_read_b128 v[202:205], v181 offset:41568
	v_mfma_f32_32x32x16_bf16 v[82:97], v[190:193], v[244:247], v[82:97]
	v_mfma_f32_32x32x16_bf16 v[66:81], v[194:197], v[244:247], v[66:81]
	ds_read_b128 v[244:247], v180 offset:9312
	s_waitcnt lgkmcnt(6)
	v_mfma_f32_32x32x16_bf16 v[50:65], v[190:193], v[206:209], v[50:65]
	v_mfma_f32_32x32x16_bf16 v[34:49], v[194:197], v[206:209], v[34:49]
	ds_read_b128 v[206:209], v180 offset:13920
	s_waitcnt lgkmcnt(6)
	v_mfma_f32_32x32x16_bf16 v[18:33], v[190:193], v[216:219], v[18:33]
	v_mfma_f32_32x32x16_bf16 v[2:17], v[194:197], v[216:219], v[2:17]
	s_waitcnt lgkmcnt(2)
	v_mfma_f32_32x32x16_bf16 v[114:129], v[198:201], v[236:239], v[114:129]
	v_mfma_f32_32x32x16_bf16 v[98:113], v[202:205], v[236:239], v[98:113]
	v_mfma_f32_32x32x16_bf16 v[82:97], v[198:201], v[240:243], v[82:97]
	v_mfma_f32_32x32x16_bf16 v[66:81], v[202:205], v[240:243], v[66:81]
	s_waitcnt lgkmcnt(1)
	v_mfma_f32_32x32x16_bf16 v[50:65], v[198:201], v[244:247], v[50:65]
	v_mfma_f32_32x32x16_bf16 v[34:49], v[202:205], v[244:247], v[34:49]
	s_waitcnt lgkmcnt(0)
	v_mfma_f32_32x32x16_bf16 v[18:33], v[198:201], v[206:209], v[18:33]
	v_mfma_f32_32x32x16_bf16 v[2:17], v[202:205], v[206:209], v[2:17]
	s_setprio 0
	s_cbranch_scc1 .Ltail_92
	s_add_i32 s21, s14, 1
	s_cmp_ge_i32 s21, s16
	s_cbranch_scc1 .Lx91_92
	s_bfe_u32 s22, s21, 0x20001
	s_bitcmp1_b32 s14, 0
	s_cselect_b64 s[4:5], -1, 0
	s_and_b64 vcc, exec, s[4:5]
	s_cbranch_vccnz .Lx89_92
	s_cmp_lt_i32 s22, 1
	s_mov_b64 s[4:5], 0xfc00000
	s_cbranch_scc1 .Lx88_92
	s_cmp_eq_u32 s22, 1
	s_mov_b64 s[8:9], -1
	s_cbranch_scc1 .Lx86_92
	s_cmp_eq_u32 s22, 2
	s_mov_b32 s4, 0x4c00000
	s_cselect_b32 s80, s4, 0x9c00000
	s_mov_b64 s[8:9], 0
	s_mov_b64 s[4:5], s[80:81]

.LcL_647:
	s_waitcnt lgkmcnt(0)
	s_barrier
	s_setprio 2
	ds_read_b128 v[178:181], v183 offset:36864
	ds_read_b128 v[194:197], v183 offset:41472
	ds_read_b128 v[206:209], v182
	ds_read_b128 v[216:219], v182 offset:4608
	ds_read_b128 v[236:239], v182 offset:9216
	ds_read_b128 v[240:243], v182 offset:13824
	ds_read_b128 v[244:247], v182 offset:32
	s_ashr_i32 s1, s0, 31
	s_lshl_b64 s[4:5], s[0:1], 7
	v_lshl_add_u64 v[154:155], v[184:185], 0, s[4:5]
	v_add_co_u32_e32 v130, vcc, 0x10000, v154
	v_lshl_add_u64 v[170:171], v[186:187], 0, s[4:5]
	s_nop 0
	v_addc_co_u32_e32 v131, vcc, 0, v155, vcc
	v_add_co_u32_e32 v134, vcc, 0x20000, v154
	global_load_dwordx4 v[142:145], v[154:155], off
	s_waitcnt lgkmcnt(4)
	v_mfma_f32_32x32x16_bf16 v[114:129], v[178:181], v[206:209], v[114:129]
	s_nop 0
	global_load_dwordx4 v[130:133], v[130:131], off
	v_addc_co_u32_e32 v135, vcc, 0, v155, vcc
	v_mfma_f32_32x32x16_bf16 v[50:65], v[194:197], v[206:209], v[50:65]
	v_add_co_u32_e32 v138, vcc, 0x30000, v154
	s_add_i32 s0, s0, 1
	s_nop 0
	ds_read_b128 v[206:209], v182 offset:4640
	ds_read_b128 v[198:201], v183 offset:36896
	ds_read_b128 v[202:205], v183 offset:41504
	s_waitcnt lgkmcnt(6)
	v_mfma_f32_32x32x16_bf16 v[98:113], v[178:181], v[216:219], v[98:113]
	v_addc_co_u32_e32 v139, vcc, 0, v155, vcc
	v_add_co_u32_e32 v146, vcc, 0x40000, v154
	global_load_dwordx4 v[134:137], v[134:135], off
	v_mfma_f32_32x32x16_bf16 v[34:49], v[194:197], v[216:219], v[34:49]
	s_nop 0
	global_load_dwordx4 v[138:141], v[138:139], off
	v_addc_co_u32_e32 v147, vcc, 0, v155, vcc
	ds_read_b128 v[216:219], v182 offset:9248
	s_waitcnt lgkmcnt(6)
	v_mfma_f32_32x32x16_bf16 v[82:97], v[178:181], v[236:239], v[82:97]
	v_add_co_u32_e32 v150, vcc, 0x50000, v154
	s_nop 0
	v_addc_co_u32_e32 v151, vcc, 0, v155, vcc
	v_mfma_f32_32x32x16_bf16 v[18:33], v[194:197], v[236:239], v[18:33]
	v_add_co_u32_e32 v156, vcc, 0x60000, v154
	global_load_dwordx4 v[146:149], v[146:147], off
	s_nop 0
	ds_read_b128 v[236:239], v182 offset:13856
	s_waitcnt lgkmcnt(6)
	v_mfma_f32_32x32x16_bf16 v[66:81], v[178:181], v[240:243], v[66:81]
	global_load_dwordx4 v[150:153], v[150:151], off
	v_addc_co_u32_e32 v157, vcc, 0, v155, vcc
	v_add_co_u32_e32 v158, vcc, 0x70000, v154
	v_mfma_f32_32x32x16_bf16 v[2:17], v[194:197], v[240:243], v[2:17]
	s_nop 1
	v_addc_co_u32_e32 v159, vcc, 0, v155, vcc
	v_add_co_u32_e32 v166, vcc, 0x10000, v170
	ds_read_b128 v[240:243], v182 offset:64
	s_waitcnt lgkmcnt(3)
	v_mfma_f32_32x32x16_bf16 v[114:129], v[198:201], v[244:247], v[114:129]
	global_load_dwordx4 v[154:157], v[156:157], off
	s_nop 0
	global_load_dwordx4 v[158:161], v[158:159], off
	v_mfma_f32_32x32x16_bf16 v[50:65], v[202:205], v[244:247], v[50:65]
	v_addc_co_u32_e32 v167, vcc, 0, v171, vcc
	v_add_co_u32_e32 v172, vcc, 0x20000, v170
	global_load_dwordx4 v[162:165], v[170:171], off
	ds_read_b128 v[244:247], v182 offset:4672
	ds_read_b128 v[178:181], v183 offset:36928
	ds_read_b128 v[194:197], v183 offset:41536
	v_mfma_f32_32x32x16_bf16 v[98:113], v[198:201], v[206:209], v[98:113]
	s_nop 0
	global_load_dwordx4 v[166:169], v[166:167], off
	v_addc_co_u32_e32 v173, vcc, 0, v171, vcc
	v_mfma_f32_32x32x16_bf16 v[34:49], v[202:205], v[206:209], v[34:49]
	v_add_co_u32_e32 v174, vcc, 0x30000, v170
	s_nop 1
	v_addc_co_u32_e32 v175, vcc, 0, v171, vcc
	ds_read_b128 v[206:209], v182 offset:9280
	s_waitcnt lgkmcnt(6)
	v_mfma_f32_32x32x16_bf16 v[82:97], v[198:201], v[216:219], v[82:97]
	global_load_dwordx4 v[170:173], v[172:173], off
	s_nop 0
	global_load_dwordx4 v[174:177], v[174:175], off
	v_mfma_f32_32x32x16_bf16 v[18:33], v[202:205], v[216:219], v[18:33]
	s_cmp_lg_u32 s0, 16
	ds_read_b128 v[216:219], v182 offset:13888
	s_waitcnt lgkmcnt(6)
	v_mfma_f32_32x32x16_bf16 v[66:81], v[198:201], v[236:239], v[66:81]
	v_mfma_f32_32x32x16_bf16 v[2:17], v[202:205], v[236:239], v[2:17]
	ds_read_b128 v[236:239], v182 offset:96
	s_waitcnt lgkmcnt(3)
	v_mfma_f32_32x32x16_bf16 v[114:129], v[178:181], v[240:243], v[114:129]
	v_mfma_f32_32x32x16_bf16 v[50:65], v[194:197], v[240:243], v[50:65]
	ds_read_b128 v[240:243], v182 offset:4704
	ds_read_b128 v[198:201], v183 offset:36960
	ds_read_b128 v[202:205], v183 offset:41568
	v_mfma_f32_32x32x16_bf16 v[98:113], v[178:181], v[244:247], v[98:113]
	v_mfma_f32_32x32x16_bf16 v[34:49], v[194:197], v[244:247], v[34:49]
	ds_read_b128 v[244:247], v182 offset:9312
	s_waitcnt lgkmcnt(6)
	v_mfma_f32_32x32x16_bf16 v[82:97], v[178:181], v[206:209], v[82:97]
	v_mfma_f32_32x32x16_bf16 v[18:33], v[194:197], v[206:209], v[18:33]
	ds_read_b128 v[206:209], v182 offset:13920
	s_waitcnt lgkmcnt(6)
	v_mfma_f32_32x32x16_bf16 v[66:81], v[178:181], v[216:219], v[66:81]
	v_mfma_f32_32x32x16_bf16 v[2:17], v[194:197], v[216:219], v[2:17]
	s_waitcnt lgkmcnt(2)
	v_mfma_f32_32x32x16_bf16 v[114:129], v[198:201], v[236:239], v[114:129]
	v_mfma_f32_32x32x16_bf16 v[50:65], v[202:205], v[236:239], v[50:65]
	v_mfma_f32_32x32x16_bf16 v[98:113], v[198:201], v[240:243], v[98:113]
	v_mfma_f32_32x32x16_bf16 v[34:49], v[202:205], v[240:243], v[34:49]
	s_waitcnt lgkmcnt(1)
	v_mfma_f32_32x32x16_bf16 v[82:97], v[198:201], v[244:247], v[82:97]
	v_mfma_f32_32x32x16_bf16 v[18:33], v[202:205], v[244:247], v[18:33]
	s_waitcnt lgkmcnt(0)
	v_mfma_f32_32x32x16_bf16 v[66:81], v[198:201], v[206:209], v[66:81]
	v_mfma_f32_32x32x16_bf16 v[2:17], v[202:205], v[206:209], v[2:17]
	s_setprio 0
	s_cbranch_scc1 .Ltail_647
	s_add_i32 s10, s10, 1
	s_cmp_ge_i32 s10, s8
	s_cbranch_scc1 .Lx646_647
	s_mul_i32 s0, s10, s82
	s_add_i32 s0, s0, s63
	s_ashr_i32 s1, s0, 31
	s_lshr_b32 s1, s1, 26
	s_add_i32 s1, s0, s1
	s_ashr_i32 s3, s1, 6
	s_andn2_b32 s1, s1, 63
	s_sub_i32 s0, s0, s1
	s_lshl_b32 s1, s3, 1
	s_and_b32 s3, s0, 1
	s_or_b32 s1, s3, s1
	v_readlane_b32 s4, v252, 35
	s_ashr_i32 s0, s0, 1
	s_sub_i32 s3, 0x7f, s1
	v_readlane_b32 s5, v252, 36
	s_and_b64 s[4:5], s[4:5], exec
	s_cselect_b32 s4, s3, s1
	s_ashr_i32 s5, s4, 31
	s_ashr_i32 s1, s0, 31
	s_lshl_b64 s[4:5], s[4:5], 19
	s_lshl_b64 s[0:1], s[0:1], 18
	v_lshl_add_u64 v[184:185], v[190:191], 0, s[4:5]
	v_lshl_add_u64 v[186:187], v[192:193], 0, s[0:1]

.LcL_801:
	s_waitcnt lgkmcnt(0)
	s_barrier
	s_setprio 2
	ds_read_b128 v[190:193], v179 offset:36864
	ds_read_b128 v[194:197], v179 offset:41472
	ds_read_b128 v[206:209], v178
	ds_read_b128 v[216:219], v178 offset:4608
	ds_read_b128 v[236:239], v178 offset:9216
	ds_read_b128 v[240:243], v178 offset:13824
	ds_read_b128 v[244:247], v178 offset:32
	s_ashr_i32 s3, s2, 31
	s_lshl_b64 s[10:11], s[2:3], 7
	v_lshl_add_u64 v[154:155], v[180:181], 0, s[10:11]
	v_add_co_u32_e32 v130, vcc, 0x2c000, v154
	v_lshl_add_u64 v[170:171], v[182:183], 0, s[10:11]
	s_nop 0
	v_addc_co_u32_e32 v131, vcc, 0, v155, vcc
	v_add_co_u32_e32 v134, vcc, 0x58000, v154
	global_load_dwordx4 v[142:145], v[154:155], off
	s_waitcnt lgkmcnt(4)
	v_mfma_f32_32x32x16_bf16 v[98:113], v[190:193], v[206:209], v[98:113]
	s_nop 0
	global_load_dwordx4 v[130:133], v[130:131], off
	v_addc_co_u32_e32 v135, vcc, 0, v155, vcc
	v_mfma_f32_32x32x16_bf16 v[114:129], v[194:197], v[206:209], v[114:129]
	v_add_co_u32_e32 v138, vcc, 0x84000, v154
	s_add_i32 s2, s2, 1
	s_nop 0
	ds_read_b128 v[206:209], v178 offset:4640
	ds_read_b128 v[198:201], v179 offset:36896
	ds_read_b128 v[202:205], v179 offset:41504
	s_waitcnt lgkmcnt(6)
	v_mfma_f32_32x32x16_bf16 v[82:97], v[190:193], v[216:219], v[82:97]
	v_addc_co_u32_e32 v139, vcc, 0, v155, vcc
	v_add_co_u32_e32 v146, vcc, 0xb0000, v154
	global_load_dwordx4 v[134:137], v[134:135], off
	v_mfma_f32_32x32x16_bf16 v[66:81], v[194:197], v[216:219], v[66:81]
	s_nop 0
	global_load_dwordx4 v[138:141], v[138:139], off
	v_addc_co_u32_e32 v147, vcc, 0, v155, vcc
	ds_read_b128 v[216:219], v178 offset:9248
	s_waitcnt lgkmcnt(6)
	v_mfma_f32_32x32x16_bf16 v[50:65], v[190:193], v[236:239], v[50:65]
	v_add_co_u32_e32 v150, vcc, 0xdc000, v154
	s_nop 0
	v_addc_co_u32_e32 v151, vcc, 0, v155, vcc
	v_mfma_f32_32x32x16_bf16 v[34:49], v[194:197], v[236:239], v[34:49]
	v_add_co_u32_e32 v156, vcc, 0x108000, v154
	global_load_dwordx4 v[146:149], v[146:147], off
	s_nop 0
	ds_read_b128 v[236:239], v178 offset:13856
	s_waitcnt lgkmcnt(6)
	v_mfma_f32_32x32x16_bf16 v[18:33], v[190:193], v[240:243], v[18:33]
	global_load_dwordx4 v[150:153], v[150:151], off
	v_addc_co_u32_e32 v157, vcc, 0, v155, vcc
	v_add_co_u32_e32 v158, vcc, 0x134000, v154
	v_mfma_f32_32x32x16_bf16 v[2:17], v[194:197], v[240:243], v[2:17]
	s_nop 1
	v_addc_co_u32_e32 v159, vcc, 0, v155, vcc
	v_add_co_u32_e32 v166, vcc, 0x2c000, v170
	ds_read_b128 v[240:243], v178 offset:64
	s_waitcnt lgkmcnt(3)
	v_mfma_f32_32x32x16_bf16 v[98:113], v[198:201], v[244:247], v[98:113]
	global_load_dwordx4 v[154:157], v[156:157], off
	s_nop 0
	global_load_dwordx4 v[158:161], v[158:159], off
	v_mfma_f32_32x32x16_bf16 v[114:129], v[202:205], v[244:247], v[114:129]
	v_addc_co_u32_e32 v167, vcc, 0, v171, vcc
	v_add_co_u32_e32 v172, vcc, 0x58000, v170
	global_load_dwordx4 v[162:165], v[170:171], off
	ds_read_b128 v[244:247], v178 offset:4672
	ds_read_b128 v[190:193], v179 offset:36928
	ds_read_b128 v[194:197], v179 offset:41536
	v_mfma_f32_32x32x16_bf16 v[82:97], v[198:201], v[206:209], v[82:97]
	s_nop 0
	global_load_dwordx4 v[166:169], v[166:167], off
	v_addc_co_u32_e32 v173, vcc, 0, v171, vcc
	v_mfma_f32_32x32x16_bf16 v[66:81], v[202:205], v[206:209], v[66:81]
	v_add_co_u32_e32 v174, vcc, 0x84000, v170
	s_nop 1
	v_addc_co_u32_e32 v175, vcc, 0, v171, vcc
	ds_read_b128 v[206:209], v178 offset:9280
	s_waitcnt lgkmcnt(6)
	v_mfma_f32_32x32x16_bf16 v[50:65], v[198:201], v[216:219], v[50:65]
	global_load_dwordx4 v[170:173], v[172:173], off
	s_nop 0
	global_load_dwordx4 v[174:177], v[174:175], off
	v_mfma_f32_32x32x16_bf16 v[34:49], v[202:205], v[216:219], v[34:49]
	s_cmp_lg_u32 s2, 44
	ds_read_b128 v[216:219], v178 offset:13888
	s_waitcnt lgkmcnt(6)
	v_mfma_f32_32x32x16_bf16 v[18:33], v[198:201], v[236:239], v[18:33]
	v_mfma_f32_32x32x16_bf16 v[2:17], v[202:205], v[236:239], v[2:17]
	ds_read_b128 v[236:239], v178 offset:96
	s_waitcnt lgkmcnt(3)
	v_mfma_f32_32x32x16_bf16 v[98:113], v[190:193], v[240:243], v[98:113]
	v_mfma_f32_32x32x16_bf16 v[114:129], v[194:197], v[240:243], v[114:129]
	ds_read_b128 v[240:243], v178 offset:4704
	ds_read_b128 v[198:201], v179 offset:36960
	ds_read_b128 v[202:205], v179 offset:41568
	v_mfma_f32_32x32x16_bf16 v[82:97], v[190:193], v[244:247], v[82:97]
	v_mfma_f32_32x32x16_bf16 v[66:81], v[194:197], v[244:247], v[66:81]
	ds_read_b128 v[244:247], v178 offset:9312
	s_waitcnt lgkmcnt(6)
	v_mfma_f32_32x32x16_bf16 v[50:65], v[190:193], v[206:209], v[50:65]
	v_mfma_f32_32x32x16_bf16 v[34:49], v[194:197], v[206:209], v[34:49]
	ds_read_b128 v[206:209], v178 offset:13920
	s_waitcnt lgkmcnt(6)
	v_mfma_f32_32x32x16_bf16 v[18:33], v[190:193], v[216:219], v[18:33]
	v_mfma_f32_32x32x16_bf16 v[2:17], v[194:197], v[216:219], v[2:17]
	s_waitcnt lgkmcnt(2)
	v_mfma_f32_32x32x16_bf16 v[98:113], v[198:201], v[236:239], v[98:113]
	v_mfma_f32_32x32x16_bf16 v[114:129], v[202:205], v[236:239], v[114:129]
	v_mfma_f32_32x32x16_bf16 v[82:97], v[198:201], v[240:243], v[82:97]
	v_mfma_f32_32x32x16_bf16 v[66:81], v[202:205], v[240:243], v[66:81]
	s_waitcnt lgkmcnt(1)
	v_mfma_f32_32x32x16_bf16 v[50:65], v[198:201], v[244:247], v[50:65]
	v_mfma_f32_32x32x16_bf16 v[34:49], v[202:205], v[244:247], v[34:49]
	s_waitcnt lgkmcnt(0)
	v_mfma_f32_32x32x16_bf16 v[18:33], v[198:201], v[206:209], v[18:33]
	v_mfma_f32_32x32x16_bf16 v[2:17], v[202:205], v[206:209], v[2:17]
	s_setprio 0
	s_cbranch_scc1 .Ltail_801
	s_add_i32 s4, s4, 1
	s_cmp_ge_i32 s4, s8
	s_cbranch_scc1 .Lz_801
	s_mul_i32 s2, s4, s82
	s_add_i32 s2, s2, s63
	s_ashr_i32 s3, s2, 31
	s_lshr_b32 s3, s3, 28
	s_add_i32 s3, s2, s3
	s_ashr_i32 s10, s3, 4
	s_and_b32 s3, s3, -16
	s_sub_i32 s2, s2, s3
	s_lshl_b32 s3, s10, 1
	s_and_b32 s10, s2, 1
	s_or_b32 s10, s10, s3
	s_lshr_b32 s11, s2, 1
	v_readlane_b32 s2, v252, 35
	s_sub_i32 s12, 0x7f, s10
	v_readlane_b32 s3, v252, 36
	s_and_b64 s[2:3], s[2:3], exec
	s_mul_i32 s2, s11, 0x58000
	s_cselect_b32 s10, s12, s10
	s_ashr_i32 s3, s2, 31
	v_mov_b32_e32 v0, 0x160000
	v_mad_i64_i32 v[180:181], s[10:11], s10, v0, v[186:187]
	v_lshl_add_u64 v[182:183], s[2:3], 1, v[188:189]

.LcL_815:
	s_waitcnt lgkmcnt(0)
	s_barrier
	s_setprio 2
	ds_read_b128 v[190:193], v179 offset:36864
	ds_read_b128 v[194:197], v179 offset:41472
	ds_read_b128 v[206:209], v178
	ds_read_b128 v[216:219], v178 offset:4608
	ds_read_b128 v[236:239], v178 offset:9216
	ds_read_b128 v[240:243], v178 offset:13824
	ds_read_b128 v[244:247], v178 offset:32
	s_ashr_i32 s1, s0, 31
	s_lshl_b64 s[8:9], s[0:1], 7
	v_lshl_add_u64 v[154:155], v[180:181], 0, s[8:9]
	v_add_co_u32_e32 v130, vcc, 0x10000, v154
	v_lshl_add_u64 v[170:171], v[182:183], 0, s[8:9]
	s_nop 0
	v_addc_co_u32_e32 v131, vcc, 0, v155, vcc
	v_add_co_u32_e32 v134, vcc, 0x20000, v154
	global_load_dwordx4 v[142:145], v[154:155], off
	s_waitcnt lgkmcnt(4)
	v_mfma_f32_32x32x16_bf16 v[114:129], v[190:193], v[206:209], v[114:129]
	s_nop 0
	global_load_dwordx4 v[130:133], v[130:131], off
	v_addc_co_u32_e32 v135, vcc, 0, v155, vcc
	v_mfma_f32_32x32x16_bf16 v[98:113], v[194:197], v[206:209], v[98:113]
	v_add_co_u32_e32 v138, vcc, 0x30000, v154
	s_add_i32 s0, s0, 1
	s_nop 0
	ds_read_b128 v[206:209], v178 offset:4640
	ds_read_b128 v[198:201], v179 offset:36896
	ds_read_b128 v[202:205], v179 offset:41504
	s_waitcnt lgkmcnt(6)
	v_mfma_f32_32x32x16_bf16 v[82:97], v[190:193], v[216:219], v[82:97]
	v_addc_co_u32_e32 v139, vcc, 0, v155, vcc
	v_add_co_u32_e32 v146, vcc, 0x40000, v154
	global_load_dwordx4 v[134:137], v[134:135], off
	v_mfma_f32_32x32x16_bf16 v[66:81], v[194:197], v[216:219], v[66:81]
	s_nop 0
	global_load_dwordx4 v[138:141], v[138:139], off
	v_addc_co_u32_e32 v147, vcc, 0, v155, vcc
	ds_read_b128 v[216:219], v178 offset:9248
	s_waitcnt lgkmcnt(6)
	v_mfma_f32_32x32x16_bf16 v[50:65], v[190:193], v[236:239], v[50:65]
	v_add_co_u32_e32 v150, vcc, 0x50000, v154
	s_nop 0
	v_addc_co_u32_e32 v151, vcc, 0, v155, vcc
	v_mfma_f32_32x32x16_bf16 v[34:49], v[194:197], v[236:239], v[34:49]
	v_add_co_u32_e32 v156, vcc, 0x60000, v154
	global_load_dwordx4 v[146:149], v[146:147], off
	s_nop 0
	ds_read_b128 v[236:239], v178 offset:13856
	s_waitcnt lgkmcnt(6)
	v_mfma_f32_32x32x16_bf16 v[18:33], v[190:193], v[240:243], v[18:33]
	global_load_dwordx4 v[150:153], v[150:151], off
	v_addc_co_u32_e32 v157, vcc, 0, v155, vcc
	v_add_co_u32_e32 v158, vcc, 0x70000, v154
	v_mfma_f32_32x32x16_bf16 v[2:17], v[194:197], v[240:243], v[2:17]
	s_nop 1
	v_addc_co_u32_e32 v159, vcc, 0, v155, vcc
	v_add_co_u32_e32 v166, vcc, 0x10000, v170
	ds_read_b128 v[240:243], v178 offset:64
	s_waitcnt lgkmcnt(3)
	v_mfma_f32_32x32x16_bf16 v[114:129], v[198:201], v[244:247], v[114:129]
	global_load_dwordx4 v[154:157], v[156:157], off
	s_nop 0
	global_load_dwordx4 v[158:161], v[158:159], off
	v_mfma_f32_32x32x16_bf16 v[98:113], v[202:205], v[244:247], v[98:113]
	v_addc_co_u32_e32 v167, vcc, 0, v171, vcc
	v_add_co_u32_e32 v172, vcc, 0x20000, v170
	global_load_dwordx4 v[162:165], v[170:171], off
	ds_read_b128 v[244:247], v178 offset:4672
	ds_read_b128 v[190:193], v179 offset:36928
	ds_read_b128 v[194:197], v179 offset:41536
	v_mfma_f32_32x32x16_bf16 v[82:97], v[198:201], v[206:209], v[82:97]
	s_nop 0
	global_load_dwordx4 v[166:169], v[166:167], off
	v_addc_co_u32_e32 v173, vcc, 0, v171, vcc
	v_mfma_f32_32x32x16_bf16 v[66:81], v[202:205], v[206:209], v[66:81]
	v_add_co_u32_e32 v174, vcc, 0x30000, v170
	s_nop 1
	v_addc_co_u32_e32 v175, vcc, 0, v171, vcc
	ds_read_b128 v[206:209], v178 offset:9280
	s_waitcnt lgkmcnt(6)
	v_mfma_f32_32x32x16_bf16 v[50:65], v[198:201], v[216:219], v[50:65]
	global_load_dwordx4 v[170:173], v[172:173], off
	s_nop 0
	global_load_dwordx4 v[174:177], v[174:175], off
	v_mfma_f32_32x32x16_bf16 v[34:49], v[202:205], v[216:219], v[34:49]
	s_cmp_lg_u32 s0, 16
	ds_read_b128 v[216:219], v178 offset:13888
	s_waitcnt lgkmcnt(6)
	v_mfma_f32_32x32x16_bf16 v[18:33], v[198:201], v[236:239], v[18:33]
	v_mfma_f32_32x32x16_bf16 v[2:17], v[202:205], v[236:239], v[2:17]
	ds_read_b128 v[236:239], v178 offset:96
	s_waitcnt lgkmcnt(3)
	v_mfma_f32_32x32x16_bf16 v[114:129], v[190:193], v[240:243], v[114:129]
	v_mfma_f32_32x32x16_bf16 v[98:113], v[194:197], v[240:243], v[98:113]
	ds_read_b128 v[240:243], v178 offset:4704
	ds_read_b128 v[198:201], v179 offset:36960
	ds_read_b128 v[202:205], v179 offset:41568
	v_mfma_f32_32x32x16_bf16 v[82:97], v[190:193], v[244:247], v[82:97]
	v_mfma_f32_32x32x16_bf16 v[66:81], v[194:197], v[244:247], v[66:81]
	ds_read_b128 v[244:247], v178 offset:9312
	s_waitcnt lgkmcnt(6)
	v_mfma_f32_32x32x16_bf16 v[50:65], v[190:193], v[206:209], v[50:65]
	v_mfma_f32_32x32x16_bf16 v[34:49], v[194:197], v[206:209], v[34:49]
	ds_read_b128 v[206:209], v178 offset:13920
	s_waitcnt lgkmcnt(6)
	v_mfma_f32_32x32x16_bf16 v[18:33], v[190:193], v[216:219], v[18:33]
	v_mfma_f32_32x32x16_bf16 v[2:17], v[194:197], v[216:219], v[2:17]
	s_waitcnt lgkmcnt(2)
	v_mfma_f32_32x32x16_bf16 v[114:129], v[198:201], v[236:239], v[114:129]
	v_mfma_f32_32x32x16_bf16 v[98:113], v[202:205], v[236:239], v[98:113]
	v_mfma_f32_32x32x16_bf16 v[82:97], v[198:201], v[240:243], v[82:97]
	v_mfma_f32_32x32x16_bf16 v[66:81], v[202:205], v[240:243], v[66:81]
	s_waitcnt lgkmcnt(1)
	v_mfma_f32_32x32x16_bf16 v[50:65], v[198:201], v[244:247], v[50:65]
	v_mfma_f32_32x32x16_bf16 v[34:49], v[202:205], v[244:247], v[34:49]
	s_waitcnt lgkmcnt(0)
	v_mfma_f32_32x32x16_bf16 v[18:33], v[198:201], v[206:209], v[18:33]
	v_mfma_f32_32x32x16_bf16 v[2:17], v[202:205], v[206:209], v[2:17]
	s_setprio 0
	s_cbranch_scc1 .Ltail_815
	s_add_i32 s2, s2, 1
	s_cmp_ge_i32 s2, s4
	s_cbranch_scc1 .Lz_815
	s_mul_i32 s0, s2, s82
	s_add_i32 s0, s0, s63
	s_mul_hi_i32 s1, s0, 0x2e8ba2e9
	s_lshr_b32 s8, s1, 31
	s_ashr_i32 s1, s1, 4
	s_add_i32 s1, s1, s8
	s_mul_i32 s8, s1, 0x58
	s_sub_i32 s0, s0, s8
	s_lshl_b32 s1, s1, 1
	s_and_b32 s8, s0, 1
	s_or_b32 s1, s8, s1
	v_readlane_b32 s8, v252, 35
	s_ashr_i32 s0, s0, 1
	s_sub_i32 s10, 0x7f, s1
	v_readlane_b32 s9, v252, 36
	s_and_b64 s[8:9], s[8:9], exec
	s_cselect_b32 s8, s10, s1
	s_ashr_i32 s9, s8, 31
	s_ashr_i32 s1, s0, 31
	s_lshl_b64 s[8:9], s[8:9], 19
	s_lshl_b64 s[0:1], s[0:1], 18
	v_lshl_add_u64 v[180:181], v[186:187], 0, s[8:9]
	v_lshl_add_u64 v[182:183], v[188:189], 0, s[0:1]
